# barrier relocation + static s_setprio 1 for waves 4-7 inside the three flash-attention unit types
# speedup vs baseline: 1.0354x; 1.0354x over previous
; #define QLOOP2(qi_, r2_, n_, ...) for (;;) { if (tid == 0) s_item = (int)atomicAdd(ctr + 64 * (qi_) + 32 * (r2_), 1u); __syncthreads(); const int item = s_item; __syncthreads(); if (item >= (n_)) break; __VA_ARGS__ }
; template <int PHM, int MIXM>
; __global__ void __launch_bounds__(512, 2) mega(Args Aval) {
;     ...
;             for (int r2 = 0; r2 < ((PROBE_DUP & 16) ? 2 : 1); ++r2) if (MIXM & 1) QLOOP2(0, r2, 256, { const int L = 15 - (item >> 4), r = item & 15; flash_unit<0>(A, l, r >> 2, r & 3, L, lds); })
.LBB0_730:
	s_setprio 0
	s_and_b64 vcc, exec, s[2:3]
	s_cbranch_vccnz .LBB0_761

; #define QLOOP2(qi_, r2_, n_, ...) for (;;) { if (tid == 0) s_item = (int)atomicAdd(ctr + 64 * (qi_) + 32 * (r2_), 1u); __syncthreads(); const int item = s_item; __syncthreads(); if (item >= (n_)) break; __VA_ARGS__ }
; template <int MODE>
; __device__ __forceinline__ void flash_unit(ArgsP A, int l, int b, int h, int qb, unsigned char* lds) {
;     ...
;     if (MODE == 0) {
;         const float csc = 0.07216878364870322f * LOG2E;
;         const bf16_t* qp = QM + (size_t)qrow * 768 + 192 * h + 8 * hh;
;         u32x4 raw[NS];
; #pragma unroll
;         for (int s = 0; s < NS; ++s) raw[s] = *(const u32x4*)(qp + 16 * s);
; #pragma unroll
;         for (int s = 0; s < 8; ++s) qf[s] = scale8(raw[s], csc);
; template <int PHM, int MIXM>
; __global__ void __launch_bounds__(512, 2) mega(Args Aval) {
;     ...
;             for (int r2 = 0; r2 < ((PROBE_DUP & 16) ? 2 : 1); ++r2) if (MIXM & 1) QLOOP2(0, r2, 256, { const int L = 15 - (item >> 4), r = item & 15; flash_unit<0>(A, l, r >> 2, r & 3, L, lds); })
.LBB0_735:
	s_or_b64 exec, exec, s[2:3]
	s_waitcnt vmcnt(0) lgkmcnt(0)
	s_barrier
	ds_read_b32 v0, v177 offset:8
	s_mov_b64 s[2:3], -1
	s_waitcnt lgkmcnt(0)
	s_barrier
	v_cmp_gt_i32_e32 vcc, s68, v0
	v_readfirstlane_b32 s4, v0
	s_cbranch_vccz .LBB0_730
	v_readfirstlane_b32 s100, v238
	s_cmp_lt_u32 s100, 0x100
	s_cbranch_scc1 .Lprio_skip_mla
	s_setprio 1
.Lprio_skip_mla:
	v_mov_b32_e32 v32, v238
	s_lshl_b32 s2, s4, 10
	v_readfirstlane_b32 s12, v32
	s_ashr_i32 s6, s12, 6
	s_load_dwordx2 s[40:41], s[26:27], 0x148
	s_and_b32 s30, s2, 0x3000
	s_lshl_b32 s2, s4, 4
	s_and_b32 s3, s2, 0xffffff00
	s_lshl_b32 s2, s6, 5
	s_sub_i32 s2, s2, s3
	v_and_b32_e32 v35, 31, v32
	s_addk_i32 s2, 0xf00
	v_or_b32_e32 v64, s2, v35
	s_and_b32 s29, s4, 3
	v_add_u32_e32 v144, s30, v64
	s_waitcnt lgkmcnt(0)
	v_mov_b64_e32 v[0:1], s[40:41]
	s_movk_i32 s4, 0x600
	v_bfe_u32 v33, v32, 5, 1
	v_mad_i64_i32 v[0:1], s[4:5], v144, s4, v[0:1]
	s_mul_i32 s18, s29, 0x180
	v_lshl_add_u64 v[0:1], v[0:1], 0, s[18:19]
	v_lshlrev_b32_e32 v176, 4, v33
	v_lshl_add_u64 v[0:1], v[0:1], 0, v[176:177]
	s_mov_b32 s4, 0x21790000
	v_add_co_u32_e32 v2, vcc, s4, v0
	s_mov_b64 s[4:5], 0x21790000
	s_nop 0
	v_addc_co_u32_e32 v3, vcc, 0, v1, vcc
	global_load_dwordx4 v[36:39], v[2:3], off
	v_lshl_add_u64 v[0:1], v[0:1], 0, s[4:5]
	global_load_dwordx4 v[40:43], v[0:1], off offset:32
	global_load_dwordx4 v[44:47], v[0:1], off offset:64
	global_load_dwordx4 v[48:51], v[0:1], off offset:96
	global_load_dwordx4 v[28:31], v[0:1], off offset:128
	global_load_dwordx4 v[24:27], v[0:1], off offset:160
	global_load_dwordx4 v[20:23], v[0:1], off offset:192
	global_load_dwordx4 v[16:19], v[0:1], off offset:224
	global_load_dwordx4 v[8:11], v[0:1], off offset:256
	global_load_dwordx4 v[4:7], v[0:1], off offset:288
	global_load_dwordx4 v[12:15], v[0:1], off offset:320
	s_nop 0
	global_load_dwordx4 v[0:3], v[0:1], off offset:352
	s_mov_b32 s14, 0x3dd53b94
	v_ashrrev_i32_e32 v145, 31, v144
	s_sub_i32 s3, 0x1000, s3
	s_add_u32 s8, s40, 0x18f90000
	v_lshlrev_b32_e32 v176, 6, v33
	s_addc_u32 s9, s41, 0
	s_lshr_b32 s31, s3, 6
	s_mov_b32 s3, 0x2e3b0000
	s_mov_b64 s[4:5], 0x2e3b0000
	s_add_u32 s10, s40, 0x22f90000
	s_addc_u32 s11, s41, 0
	v_and_b32_e32 v34, 63, v32
	s_add_i32 s16, s6, 8
	s_add_i32 s17, s6, 16
	s_mov_b32 s7, 0x2aaaaaab
	s_lshl_b32 s18, s29, 9
	s_mov_b64 s[20:21], 0x800
	s_lshl_b32 s27, s6, 10
	s_lshl_b32 s34, s16, 10
	v_lshlrev_b32_e32 v164, 2, v33
	s_mov_b32 s43, 0
	s_mov_b64 s[38:39], 0x800
	v_mov_b32_e32 v171, 0
	v_mov_b32_e32 v172, 0xff800000
	s_waitcnt vmcnt(10)
	v_lshlrev_b32_e32 v56, 16, v40
	v_lshlrev_b32_e32 v52, 16, v36
	v_and_b32_e32 v53, 0xffff0000, v36
	v_lshlrev_b32_e32 v36, 16, v37
	v_and_b32_e32 v37, 0xffff0000, v37
	v_pk_mul_f32 v[36:37], v[36:37], s[14:15] op_sel_hi:[1,0]
	v_and_b32_e32 v57, 0xffff0000, v40
	v_cvt_pk_bf16_f32 v97, v36, v37
	s_waitcnt vmcnt(8)
	v_lshlrev_b32_e32 v36, 16, v48
	v_and_b32_e32 v37, 0xffff0000, v48
	v_pk_mul_f32 v[36:37], v[36:37], s[14:15] op_sel_hi:[1,0]
	v_lshlrev_b32_e32 v40, 16, v41
	v_cvt_pk_bf16_f32 v108, v36, v37
	v_lshlrev_b32_e32 v36, 16, v49
	v_and_b32_e32 v37, 0xffff0000, v49
	v_pk_mul_f32 v[36:37], v[36:37], s[14:15] op_sel_hi:[1,0]
	v_and_b32_e32 v41, 0xffff0000, v41
	v_cvt_pk_bf16_f32 v109, v36, v37
	v_lshlrev_b32_e32 v36, 16, v50
	v_and_b32_e32 v37, 0xffff0000, v50
	v_pk_mul_f32 v[36:37], v[36:37], s[14:15] op_sel_hi:[1,0]
	v_pk_mul_f32 v[40:41], v[40:41], s[14:15] op_sel_hi:[1,0]
	v_cvt_pk_bf16_f32 v110, v36, v37
	v_lshlrev_b32_e32 v36, 16, v51
	v_and_b32_e32 v37, 0xffff0000, v51
	v_cvt_pk_bf16_f32 v101, v40, v41
	v_pk_mul_f32 v[40:41], v[36:37], s[14:15] op_sel_hi:[1,0]
	v_lshlrev_b32_e32 v58, 16, v42
	v_cvt_pk_bf16_f32 v111, v40, v41
	s_waitcnt vmcnt(7)
	v_lshlrev_b32_e32 v40, 16, v28
	v_and_b32_e32 v41, 0xffff0000, v28
	v_lshlrev_b32_e32 v28, 16, v29
	v_and_b32_e32 v29, 0xffff0000, v29
	v_pk_mul_f32 v[28:29], v[28:29], s[14:15] op_sel_hi:[1,0]
	v_and_b32_e32 v59, 0xffff0000, v42
	v_cvt_pk_bf16_f32 v113, v28, v29
	v_lshlrev_b32_e32 v28, 16, v30
	v_and_b32_e32 v29, 0xffff0000, v30
	v_lshlrev_b32_e32 v42, 16, v43
	v_and_b32_e32 v43, 0xffff0000, v43
	v_lshlrev_b64 v[36:37], 8, v[144:145]
	v_pk_mul_f32 v[28:29], v[28:29], s[14:15] op_sel_hi:[1,0]
	v_pk_mul_f32 v[42:43], v[42:43], s[14:15] op_sel_hi:[1,0]
	v_lshl_add_u64 v[36:37], s[40:41], 0, v[36:37]
	v_cvt_pk_bf16_f32 v114, v28, v29
	v_lshlrev_b32_e32 v28, 16, v31
	v_and_b32_e32 v29, 0xffff0000, v31
	v_cvt_pk_bf16_f32 v103, v42, v43
	v_lshl_add_u64 v[42:43], v[36:37], 0, v[176:177]
	v_pk_mul_f32 v[28:29], v[28:29], s[14:15] op_sel_hi:[1,0]
	v_lshlrev_b32_e32 v54, 16, v38
	v_and_b32_e32 v55, 0xffff0000, v38
	v_lshlrev_b32_e32 v38, 16, v39
	v_and_b32_e32 v39, 0xffff0000, v39
	v_add_co_u32_e32 v36, vcc, s3, v42
	v_cvt_pk_bf16_f32 v115, v28, v29
	s_waitcnt vmcnt(6)
	v_lshlrev_b32_e32 v28, 16, v24
	v_and_b32_e32 v29, 0xffff0000, v24
	v_pk_mul_f32 v[38:39], v[38:39], s[14:15] op_sel_hi:[1,0]
	v_addc_co_u32_e32 v37, vcc, 0, v43, vcc
	v_pk_mul_f32 v[28:29], v[28:29], s[14:15] op_sel_hi:[1,0]
	v_lshlrev_b32_e32 v60, 16, v44
	v_and_b32_e32 v61, 0xffff0000, v44
	v_lshlrev_b32_e32 v44, 16, v45
	v_and_b32_e32 v45, 0xffff0000, v45
	v_lshlrev_b32_e32 v62, 16, v46
	v_and_b32_e32 v63, 0xffff0000, v46
	v_lshlrev_b32_e32 v46, 16, v47
	v_and_b32_e32 v47, 0xffff0000, v47
	v_cvt_pk_bf16_f32 v99, v38, v39
	global_load_dwordx4 v[36:39], v[36:37], off
	v_cvt_pk_bf16_f32 v116, v28, v29
	v_lshlrev_b32_e32 v24, 16, v25
	v_and_b32_e32 v25, 0xffff0000, v25
	s_waitcnt vmcnt(6)
; __device__ __forceinline__ unsigned cvt_pk(float lo, float hi) { f32x2_t v = {lo, hi}; bf16x2_t b = __builtin_convertvector(v, bf16x2_t); return __builtin_bit_cast(unsigned, b); }
; __device__ __forceinline__ float bflo(unsigned w) { return __uint_as_float(w << 16); }
; __device__ __forceinline__ float bfhi(unsigned w) { return __uint_as_float(w & 0xffff0000u); }
; template <int MODE>
; __device__ __forceinline__ void flash_unit(ArgsP A, int l, int b, int h, int qb, unsigned char* lds) {
;     ...
;         for (int s = 0; s < 8; ++s) qf[s] = scale8(raw[s], csc);
;         const float* rope = (const float*)(A->ws + WS_ROPE) + (size_t)qrow * 64;
; #pragma unroll
;         for (int pr = 0; pr < 2; ++pr) {
;             const u32x4 xa = raw[8 + pr], xb = raw[10 + pr]; const f32x4* cs = (const f32x4*)(rope + 2 * (16 * pr + 8 * hh));
;             float a[8], bb[8], oa[8], ob[8];
;             a[0] = bflo(xa.x); a[1] = bfhi(xa.x); a[2] = bflo(xa.y); a[3] = bfhi(xa.y); a[4] = bflo(xa.z); a[5] = bfhi(xa.z); a[6] = bflo(xa.w); a[7] = bfhi(xa.w);
;             bb[0] = bflo(xb.x); bb[1] = bfhi(xb.x); bb[2] = bflo(xb.y); bb[3] = bfhi(xb.y); bb[4] = bflo(xb.z); bb[5] = bfhi(xb.z); bb[6] = bflo(xb.w); bb[7] = bfhi(xb.w);
; #pragma unroll
;             for (int jj = 0; jj < 4; ++jj) { const f32x4 t4 = cs[jj];
;                 oa[2 * jj] = (a[2 * jj] * t4[0] - bb[2 * jj] * t4[1]) * csc; ob[2 * jj] = (a[2 * jj] * t4[1] + bb[2 * jj] * t4[0]) * csc;
;                 oa[2 * jj + 1] = (a[2 * jj + 1] * t4[2] - bb[2 * jj + 1] * t4[3]) * csc; ob[2 * jj + 1] = (a[2 * jj + 1] * t4[3] + bb[2 * jj + 1] * t4[2]) * csc; }
;             u32x4 wa, wb; wa.x = cvt_pk(oa[0], oa[1]); wa.y = cvt_pk(oa[2], oa[3]); wa.z = cvt_pk(oa[4], oa[5]); wa.w = cvt_pk(oa[6], oa[7]);
;             wb.x = cvt_pk(ob[0], ob[1]); wb.y = cvt_pk(ob[2], ob[3]); wb.z = cvt_pk(ob[4], ob[5]); wb.w = cvt_pk(ob[6], ob[7]);
;             qf[8 + pr] = __builtin_bit_cast(bf16x8, wa); qf[10 + pr] = __builtin_bit_cast(bf16x8, wb);
	v_lshlrev_b32_e32 v28, 16, v20
	v_and_b32_e32 v29, 0xffff0000, v20
	v_lshlrev_b32_e32 v20, 16, v21
	v_and_b32_e32 v21, 0xffff0000, v21
	v_pk_mul_f32 v[44:45], v[44:45], s[14:15] op_sel_hi:[1,0]
	v_pk_mul_f32 v[46:47], v[46:47], s[14:15] op_sel_hi:[1,0]
	v_pk_mul_f32 v[40:41], v[40:41], s[14:15] op_sel_hi:[1,0]
	v_lshl_add_u64 v[48:49], v[42:43], 0, s[4:5]
	v_pk_mul_f32 v[24:25], v[24:25], s[14:15] op_sel_hi:[1,0]
	v_pk_mul_f32 v[20:21], v[20:21], s[14:15] op_sel_hi:[1,0]
	v_cvt_pk_bf16_f32 v105, v44, v45
	v_cvt_pk_bf16_f32 v107, v46, v47
	v_cvt_pk_bf16_f32 v112, v40, v41
	global_load_dwordx4 v[40:43], v[48:49], off offset:32
	global_load_dwordx4 v[44:47], v[48:49], off offset:16
	v_cvt_pk_bf16_f32 v117, v24, v25
	v_lshlrev_b32_e32 v24, 16, v26
	v_and_b32_e32 v25, 0xffff0000, v26
	v_cvt_pk_bf16_f32 v121, v20, v21
	v_lshlrev_b32_e32 v20, 16, v22
	v_and_b32_e32 v21, 0xffff0000, v22
	v_pk_mul_f32 v[24:25], v[24:25], s[14:15] op_sel_hi:[1,0]
	v_pk_mul_f32 v[20:21], v[20:21], s[14:15] op_sel_hi:[1,0]
	v_cvt_pk_bf16_f32 v118, v24, v25
	v_lshlrev_b32_e32 v24, 16, v27
	v_and_b32_e32 v25, 0xffff0000, v27
	v_cvt_pk_bf16_f32 v122, v20, v21
	v_lshlrev_b32_e32 v20, 16, v23
	v_and_b32_e32 v21, 0xffff0000, v23
	v_pk_mul_f32 v[24:25], v[24:25], s[14:15] op_sel_hi:[1,0]
	v_pk_mul_f32 v[20:21], v[20:21], s[14:15] op_sel_hi:[1,0]
	v_cvt_pk_bf16_f32 v119, v24, v25
	global_load_dwordx4 v[24:27], v[48:49], off offset:48
	v_cvt_pk_bf16_f32 v123, v20, v21
	s_waitcnt vmcnt(8)
	v_lshlrev_b32_e32 v20, 16, v16
	v_and_b32_e32 v21, 0xffff0000, v16
	v_lshlrev_b32_e32 v16, 16, v17
	v_and_b32_e32 v17, 0xffff0000, v17
	v_pk_mul_f32 v[16:17], v[16:17], s[14:15] op_sel_hi:[1,0]
	v_pk_mul_f32 v[20:21], v[20:21], s[14:15] op_sel_hi:[1,0]
	v_cvt_pk_bf16_f32 v125, v16, v17
	v_lshlrev_b32_e32 v16, 16, v18
	v_and_b32_e32 v17, 0xffff0000, v18
	v_pk_mul_f32 v[16:17], v[16:17], s[14:15] op_sel_hi:[1,0]
	v_cvt_pk_bf16_f32 v124, v20, v21
	global_load_dwordx4 v[20:23], v[48:49], off offset:128
	v_cvt_pk_bf16_f32 v126, v16, v17
	v_lshlrev_b32_e32 v16, 16, v19
	v_and_b32_e32 v17, 0xffff0000, v19
	v_pk_mul_f32 v[28:29], v[28:29], s[14:15] op_sel_hi:[1,0]
	v_pk_mul_f32 v[16:17], v[16:17], s[14:15] op_sel_hi:[1,0]
	v_cvt_pk_bf16_f32 v120, v28, v29
	v_cvt_pk_bf16_f32 v127, v16, v17
	global_load_dwordx4 v[16:19], v[48:49], off offset:160
	global_load_dwordx4 v[28:31], v[48:49], off offset:144
	v_pk_mul_f32 v[54:55], v[54:55], s[14:15] op_sel_hi:[1,0]
	global_load_dwordx4 v[48:51], v[48:49], off offset:176
	v_pk_mul_f32 v[56:57], v[56:57], s[14:15] op_sel_hi:[1,0]
	v_pk_mul_f32 v[52:53], v[52:53], s[14:15] op_sel_hi:[1,0]
	v_cvt_pk_bf16_f32 v98, v54, v55
	v_cvt_pk_bf16_f32 v100, v56, v57
	s_waitcnt vmcnt(9)
	v_lshlrev_b32_e32 v54, 16, v12
	v_and_b32_e32 v55, 0xffff0000, v12
	v_cvt_pk_bf16_f32 v96, v52, v53
	v_lshlrev_b32_e32 v52, 16, v8
	v_and_b32_e32 v53, 0xffff0000, v8
	v_lshlrev_b32_e32 v12, 16, v13
	v_and_b32_e32 v13, 0xffff0000, v13
	v_lshlrev_b32_e32 v8, 16, v9
	v_and_b32_e32 v9, 0xffff0000, v9
	v_pk_mul_f32 v[58:59], v[58:59], s[14:15] op_sel_hi:[1,0]
	v_pk_mul_f32 v[60:61], v[60:61], s[14:15] op_sel_hi:[1,0]
	v_pk_mul_f32 v[62:63], v[62:63], s[14:15] op_sel_hi:[1,0]
	s_ashr_i32 s3, s2, 31
	v_cvt_pk_bf16_f32 v102, v58, v59
	v_cvt_pk_bf16_f32 v104, v60, v61
	v_cvt_pk_bf16_f32 v106, v62, v63
	s_lshr_b32 s3, s3, 26
	s_waitcnt vmcnt(7)
	v_mov_b32_e32 v56, v36
	v_mov_b32_e32 v57, v38
	v_mov_b32_e32 v38, v37
	v_pk_mul_f32 v[36:37], v[38:39], v[54:55]
	v_pk_mul_f32 v[54:55], v[56:57], v[54:55]
	v_pk_fma_f32 v[36:37], v[56:57], v[52:53], v[36:37] neg_lo:[0,0,1] neg_hi:[0,0,1]
	v_pk_fma_f32 v[38:39], v[38:39], v[52:53], v[54:55]
	v_pk_mul_f32 v[36:37], v[36:37], s[14:15] op_sel_hi:[1,0]
	v_pk_mul_f32 v[38:39], v[38:39], s[14:15] op_sel_hi:[1,0]
	v_cvt_pk_bf16_f32 v128, v36, v37
	v_cvt_pk_bf16_f32 v132, v38, v39
	s_waitcnt vmcnt(5)
	v_mov_b32_e32 v52, v44
	v_mov_b32_e32 v53, v46
	v_mov_b32_e32 v46, v45
	v_pk_mul_f32 v[44:45], v[46:47], v[12:13]
	v_pk_mul_f32 v[12:13], v[52:53], v[12:13]
	v_pk_fma_f32 v[44:45], v[52:53], v[8:9], v[44:45] neg_lo:[0,0,1] neg_hi:[0,0,1]
	v_pk_fma_f32 v[8:9], v[46:47], v[8:9], v[12:13]
	v_lshlrev_b32_e32 v46, 16, v14
	v_and_b32_e32 v47, 0xffff0000, v14
	v_mov_b32_e32 v52, v40
	v_mov_b32_e32 v53, v42
	v_mov_b32_e32 v42, v41
	v_lshlrev_b32_e32 v12, 16, v10
	v_and_b32_e32 v13, 0xffff0000, v10
	v_pk_mul_f32 v[40:41], v[42:43], v[46:47]
	v_pk_mul_f32 v[46:47], v[52:53], v[46:47]
	v_pk_fma_f32 v[40:41], v[52:53], v[12:13], v[40:41] neg_lo:[0,0,1] neg_hi:[0,0,1]
	v_pk_fma_f32 v[12:13], v[42:43], v[12:13], v[46:47]
	v_lshlrev_b32_e32 v14, 16, v15
	v_and_b32_e32 v15, 0xffff0000, v15
	s_waitcnt vmcnt(4)
	v_mov_b32_e32 v42, v24
	v_mov_b32_e32 v43, v26
	v_mov_b32_e32 v26, v25
	v_lshlrev_b32_e32 v10, 16, v11
	v_and_b32_e32 v11, 0xffff0000, v11
	v_pk_mul_f32 v[24:25], v[26:27], v[14:15]
	v_pk_mul_f32 v[14:15], v[42:43], v[14:15]
	v_pk_fma_f32 v[24:25], v[42:43], v[10:11], v[24:25] neg_lo:[0,0,1] neg_hi:[0,0,1]
	v_pk_fma_f32 v[10:11], v[26:27], v[10:11], v[14:15]
	v_pk_mul_f32 v[12:13], v[12:13], s[14:15] op_sel_hi:[1,0]
	v_pk_mul_f32 v[10:11], v[10:11], s[14:15] op_sel_hi:[1,0]
	v_pk_mul_f32 v[8:9], v[8:9], s[14:15] op_sel_hi:[1,0]
	v_cvt_pk_bf16_f32 v134, v12, v13
	v_cvt_pk_bf16_f32 v135, v10, v11
	v_lshlrev_b32_e32 v10, 16, v0
	v_and_b32_e32 v11, 0xffff0000, v0
	s_waitcnt vmcnt(3)
	v_mov_b32_e32 v12, v20
	v_mov_b32_e32 v13, v22
	v_mov_b32_e32 v22, v21
	v_cvt_pk_bf16_f32 v133, v8, v9
	v_lshlrev_b32_e32 v8, 16, v4
	v_and_b32_e32 v9, 0xffff0000, v4
	v_pk_mul_f32 v[14:15], v[22:23], v[10:11]
	v_pk_mul_f32 v[10:11], v[12:13], v[10:11]
	v_pk_fma_f32 v[14:15], v[12:13], v[8:9], v[14:15] neg_lo:[0,0,1] neg_hi:[0,0,1]
	v_pk_fma_f32 v[8:9], v[22:23], v[8:9], v[10:11]
	v_lshlrev_b32_e32 v0, 16, v1
	v_and_b32_e32 v1, 0xffff0000, v1
	s_waitcnt vmcnt(1)
; template <int MODE>
; __device__ __forceinline__ void flash_unit(ArgsP A, int l, int b, int h, int qb, unsigned char* lds) {
;     ...
;                 oa[2 * jj + 1] = (a[2 * jj + 1] * t4[2] - bb[2 * jj + 1] * t4[3]) * csc; ob[2 * jj + 1] = (a[2 * jj + 1] * t4[3] + bb[2 * jj + 1] * t4[2]) * csc; }
;             u32x4 wa, wb; wa.x = cvt_pk(oa[0], oa[1]); wa.y = cvt_pk(oa[2], oa[3]); wa.z = cvt_pk(oa[4], oa[5]); wa.w = cvt_pk(oa[6], oa[7]);
;             wb.x = cvt_pk(ob[0], ob[1]); wb.y = cvt_pk(ob[2], ob[3]); wb.z = cvt_pk(ob[4], ob[5]); wb.w = cvt_pk(ob[6], ob[7]);
;             qf[8 + pr] = __builtin_bit_cast(bf16x8, wa); qf[10 + pr] = __builtin_bit_cast(bf16x8, wb);
;     ...
;     int kbase[4];
; #pragma unroll
;     for (int bsel = 0; bsel < 4; ++bsel) { const int ch = 2 * bsel + hh + (MODE == 1 ? 8 * map : 0), xr = (MODE == 1) ? (q32 & 15) : ((q32 >> 1) & 7); kbase[bsel] = (q32 * KCH + (ch ^ xr)) * 16; }
;     auto dma_tile = [&](int t) {
;         const int kr0 = rowbase + 64 * t;
;         const int slot = t % NBUF; const unsigned kb_ = lds0 + slot * KBYTES, vb_ = lds0 + NBUF * KBYTES + slot * VBYTES;
; #pragma unroll
;         for (int i = 0; i < NKI; ++i) { const int piece = wave + 8 * i, p = 64 * piece + lane, key = p / KCH, cs = p % KCH;
;             const int ch = cs ^ (MODE == 1 ? (key & 15) : ((key >> 1) & 7)); const bf16_t* src;
;             if (MODE == 0) src = (ch < 16) ? KVM + (size_t)(kr0 + key) * 1024 + 256 * h + 8 * ch : PROJ + (size_t)(kr0 + key) * INWP + C_KR + 8 * (ch - 16);
;             else if (MODE == 1) src = PROJ + (size_t)(kr0 + key) * INWP + C_DK + 128 * h + 8 * ch;
;             else src = PROJ + (size_t)(kr0 + key) * INWP + C_RK + 64 * h + 8 * ch;
;             glds16(src, (unsigned)__builtin_amdgcn_readfirstlane(kb_ + piece * 1024)); }
; #pragma unroll
;         for (int i = 0; i < 2; ++i) { const int piece = wave + 8 * i, p = 64 * piece + lane, st = p >> 5, key = 8 * (st >> 2) + ((p & 31) >> 2), col = 32 * (st & 3) + 8 * (p & 3); const bf16_t* src;
;             if (MODE == 0) src = KVM + (size_t)(kr0 + key) * 1024 + 256 * h + 128 + col;
;             else if (MODE == 1) src = PROJ + (size_t)(kr0 + key) * INWP + C_DV + 128 * h + col;
;             else src = PROJ + (size_t)(kr0 + key) * INWP + C_RV + 128 * h + col;
;             glds16(src, (unsigned)__builtin_amdgcn_readfirstlane(vb_ + piece * 1024)); }
	v_mov_b32_e32 v11, v30
	v_mov_b32_e32 v30, v29
	v_lshlrev_b32_e32 v4, 16, v5
	v_and_b32_e32 v5, 0xffff0000, v5
	v_mov_b32_e32 v10, v28
	v_pk_mul_f32 v[12:13], v[30:31], v[0:1]
	v_pk_mul_f32 v[0:1], v[10:11], v[0:1]
	v_pk_fma_f32 v[12:13], v[10:11], v[4:5], v[12:13] neg_lo:[0,0,1] neg_hi:[0,0,1]
	v_lshlrev_b32_e32 v10, 16, v2
	v_and_b32_e32 v11, 0xffff0000, v2
	v_mov_b32_e32 v20, v16
	v_mov_b32_e32 v21, v18
	v_mov_b32_e32 v18, v17
	v_pk_fma_f32 v[0:1], v[30:31], v[4:5], v[0:1]
	v_lshlrev_b32_e32 v4, 16, v6
	v_and_b32_e32 v5, 0xffff0000, v6
	v_pk_mul_f32 v[16:17], v[18:19], v[10:11]
	v_pk_mul_f32 v[10:11], v[20:21], v[10:11]
	v_pk_fma_f32 v[16:17], v[20:21], v[4:5], v[16:17] neg_lo:[0,0,1] neg_hi:[0,0,1]
	v_pk_fma_f32 v[4:5], v[18:19], v[4:5], v[10:11]
	v_lshlrev_b32_e32 v2, 16, v3
	v_and_b32_e32 v3, 0xffff0000, v3
	s_waitcnt vmcnt(0)
	v_mov_b32_e32 v10, v48
	v_mov_b32_e32 v11, v50
	v_mov_b32_e32 v50, v49
	v_lshlrev_b32_e32 v6, 16, v7
	v_and_b32_e32 v7, 0xffff0000, v7
	v_pk_mul_f32 v[18:19], v[50:51], v[2:3]
	v_pk_mul_f32 v[2:3], v[10:11], v[2:3]
	v_pk_mul_f32 v[0:1], v[0:1], s[14:15] op_sel_hi:[1,0]
	v_pk_fma_f32 v[2:3], v[50:51], v[6:7], v[2:3]
	v_cvt_pk_bf16_f32 v141, v0, v1
	v_pk_mul_f32 v[2:3], v[2:3], s[14:15] op_sel_hi:[1,0]
	v_bfe_u32 v0, v32, 1, 3
	v_mul_u32_u24_e32 v1, 24, v35
	v_cvt_pk_bf16_f32 v143, v2, v3
	v_bitop3_b32 v2, v33, v1, v0 bitop3:0xde
	v_lshlrev_b32_e32 v160, 4, v2
	v_or_b32_e32 v2, 2, v33
	v_bitop3_b32 v2, v2, v1, v0 bitop3:0xde
	v_lshlrev_b32_e32 v161, 4, v2
	v_or_b32_e32 v2, 4, v33
	v_bitop3_b32 v2, v2, v1, v0 bitop3:0xde
	v_pk_fma_f32 v[18:19], v[10:11], v[6:7], v[18:19] neg_lo:[0,0,1] neg_hi:[0,0,1]
	v_lshlrev_b32_e32 v162, 4, v2
	v_or_b32_e32 v2, 6, v33
	v_pk_mul_f32 v[44:45], v[44:45], s[14:15] op_sel_hi:[1,0]
	v_pk_mul_f32 v[40:41], v[40:41], s[14:15] op_sel_hi:[1,0]
	v_pk_mul_f32 v[24:25], v[24:25], s[14:15] op_sel_hi:[1,0]
	v_pk_mul_f32 v[14:15], v[14:15], s[14:15] op_sel_hi:[1,0]
	v_pk_mul_f32 v[8:9], v[8:9], s[14:15] op_sel_hi:[1,0]
	v_pk_mul_f32 v[12:13], v[12:13], s[14:15] op_sel_hi:[1,0]
	v_pk_mul_f32 v[16:17], v[16:17], s[14:15] op_sel_hi:[1,0]
	v_pk_mul_f32 v[4:5], v[4:5], s[14:15] op_sel_hi:[1,0]
	v_pk_mul_f32 v[18:19], v[18:19], s[14:15] op_sel_hi:[1,0]
	v_bitop3_b32 v0, v2, v1, v0 bitop3:0xde
	v_cvt_pk_bf16_f32 v129, v44, v45
	v_cvt_pk_bf16_f32 v130, v40, v41
	v_cvt_pk_bf16_f32 v131, v24, v25
	v_cvt_pk_bf16_f32 v136, v14, v15
	v_cvt_pk_bf16_f32 v137, v12, v13
	v_cvt_pk_bf16_f32 v138, v16, v17
	v_cvt_pk_bf16_f32 v139, v18, v19
	v_cvt_pk_bf16_f32 v140, v8, v9
	v_cvt_pk_bf16_f32 v142, v4, v5
	v_lshlrev_b32_e32 v163, 4, v0
	v_mov_b32_e32 v0, v177
	v_mov_b32_e32 v1, v177
	v_mov_b32_e32 v2, v177
	s_add_i32 s2, s3, s2
	s_add_i32 s13, s2, 31
	v_mov_b32_e32 v0, s12
	s_movk_i32 s2, 0xffc0
	v_bfi_b32 v24, s2, v0, v32
	v_lshl_or_b32 v28, s16, 6, v34
	v_lshl_or_b32 v18, s17, 6, v34
	v_mul_hi_i32 v0, v24, s7
	v_mul_hi_i32 v10, v28, s7
	v_mul_hi_i32 v19, v18, s7
	v_lshrrev_b32_e32 v1, 31, v0
	v_ashrrev_i32_e32 v0, 2, v0
	v_lshrrev_b32_e32 v11, 31, v10
	v_ashrrev_i32_e32 v10, 2, v10
	v_lshrrev_b32_e32 v20, 31, v19
	v_ashrrev_i32_e32 v19, 2, v19
	v_add_u32_e32 v25, v0, v1
	v_add_u32_e32 v35, v10, v11
	v_add_u32_e32 v34, v19, v20
	v_mul_lo_u32 v0, v25, 24
	v_mul_lo_u32 v10, v35, 24
	v_mul_lo_u32 v19, v34, 24
	v_sub_u32_e32 v0, v24, v0
	v_lshrrev_b32_e32 v1, 1, v25
	v_sub_u32_e32 v10, v28, v10
	v_lshrrev_b32_e32 v11, 1, v35
	v_sub_u32_e32 v18, v18, v19
	v_lshrrev_b32_e32 v19, 1, v34
	v_bitop3_b32 v29, v1, v0, 7 bitop3:0x6c
	v_add_u32_e32 v0, s30, v25
	v_mov_b64_e32 v[2:3], s[8:9]
	v_bitop3_b32 v36, v11, v10, 7 bitop3:0x6c
	v_add_u32_e32 v10, s30, v35
	v_bitop3_b32 v37, v19, v18, 7 bitop3:0x6c
	v_add_u32_e32 v18, s30, v34
	v_mad_i64_i32 v[4:5], s[4:5], v0, s35, v[2:3]
	v_mad_i64_i32 v[12:13], s[14:15], v10, s35, v[2:3]
	v_mad_i64_i32 v[2:3], s[14:15], v18, s35, v[2:3]
	s_ashr_i32 s12, s12, 4
	v_bfe_u32 v38, v32, 2, 3
	s_and_b32 s12, s12, -8
	v_lshlrev_b32_e32 v26, 3, v32
	v_or_b32_e32 v30, s30, v38
	s_lshl_b32 s14, s16, 2
	v_and_b32_e32 v39, 24, v26
	v_add_u32_e32 v26, s12, v30
	s_and_b32 s14, s14, -8
	v_ashrrev_i32_e32 v1, 31, v0
	v_lshlrev_b32_e32 v176, 3, v29
	v_ashrrev_i32_e32 v27, 31, v26
	v_add_u32_e32 v30, s14, v30
	v_lshlrev_b64 v[6:7], 1, v[176:177]
	v_lshlrev_b64 v[0:1], 11, v[0:1]
	v_ashrrev_i32_e32 v9, 31, v176
	v_mov_b32_e32 v8, v176
	v_ashrrev_i32_e32 v11, 31, v10
	v_lshlrev_b32_e32 v176, 3, v36
	s_movk_i32 s15, 0x60
	v_lshlrev_b64 v[26:27], 11, v[26:27]
	v_ashrrev_i32_e32 v31, 31, v30
	v_lshl_add_u64 v[0:1], s[10:11], 0, v[0:1]
	v_lshlrev_b64 v[14:15], 1, v[176:177]
	v_lshlrev_b64 v[10:11], 11, v[10:11]
	v_ashrrev_i32_e32 v17, 31, v176
	v_mov_b32_e32 v16, v176
	v_ashrrev_i32_e32 v19, 31, v18
	v_lshlrev_b32_e32 v176, 3, v37
	v_and_or_b32 v24, v24, s15, v39
	v_lshl_add_u64 v[26:27], s[10:11], 0, v[26:27]
	v_lshlrev_b64 v[30:31], 11, v[30:31]
	s_ashr_i32 s26, s13, 6
	v_lshl_add_u64 v[4:5], v[4:5], 0, v[6:7]
	v_lshl_add_u64 v[0:1], v[0:1], 0, s[18:19]
	v_lshlrev_b64 v[8:9], 1, v[8:9]
	v_lshl_add_u64 v[10:11], s[10:11], 0, v[10:11]
	v_lshlrev_b64 v[20:21], 1, v[176:177]
	v_lshlrev_b64 v[18:19], 11, v[18:19]
	v_ashrrev_i32_e32 v23, 31, v176
	v_mov_b32_e32 v22, v176
	v_lshl_add_u64 v[26:27], v[26:27], 0, s[18:19]
	v_lshlrev_b32_e32 v176, 1, v24
	v_and_or_b32 v28, v28, s15, v39
	v_lshl_add_u64 v[30:31], s[10:11], 0, v[30:31]
	v_lshl_add_u64 v[4:5], v[4:5], 0, s[20:21]
	v_lshl_add_u64 v[0:1], v[0:1], 0, v[8:9]
	v_lshl_add_u64 v[12:13], v[12:13], 0, v[14:15]
	v_lshl_add_u64 v[10:11], v[10:11], 0, s[18:19]
	v_lshlrev_b64 v[16:17], 1, v[16:17]
	v_lshl_add_u64 v[2:3], v[2:3], 0, v[20:21]
	v_lshl_add_u64 v[18:19], s[10:11], 0, v[18:19]
	v_lshl_add_u64 v[26:27], v[26:27], 0, v[176:177]
	v_lshl_add_u64 v[30:31], v[30:31], 0, s[18:19]
	v_lshlrev_b32_e32 v176, 1, v28
	v_cmp_gt_i32_e32 vcc, 16, v29
	s_cmp_lg_u32 16, -1
	v_lshl_add_u64 v[12:13], v[12:13], 0, s[20:21]
	v_lshl_add_u64 v[10:11], v[10:11], 0, v[16:17]
	v_lshl_add_u64 v[2:3], v[2:3], 0, s[20:21]
	v_lshl_add_u64 v[18:19], v[18:19], 0, s[18:19]
	v_lshlrev_b64 v[22:23], 1, v[22:23]
	s_mov_b64 s[20:21], 0x100
	v_lshl_add_u64 v[30:31], v[30:31], 0, v[176:177]
	v_cndmask_b32_e32 v1, v5, v1, vcc
	v_cndmask_b32_e32 v0, v4, v0, vcc
	s_cselect_b32 s15, 16, 0
	v_cmp_gt_i32_e32 vcc, 16, v36
	s_barrier
; template <int MODE>
; __device__ __forceinline__ void flash_unit(ArgsP A, int l, int b, int h, int qb, unsigned char* lds) {
;     ...
;     auto dma_tile = [&](int t) {
;         const int kr0 = rowbase + 64 * t;
;         const int slot = t % NBUF; const unsigned kb_ = lds0 + slot * KBYTES, vb_ = lds0 + NBUF * KBYTES + slot * VBYTES;
; #pragma unroll
;         for (int i = 0; i < NKI; ++i) { const int piece = wave + 8 * i, p = 64 * piece + lane, key = p / KCH, cs = p % KCH;
;             const int ch = cs ^ (MODE == 1 ? (key & 15) : ((key >> 1) & 7)); const bf16_t* src;
;             if (MODE == 0) src = (ch < 16) ? KVM + (size_t)(kr0 + key) * 1024 + 256 * h + 8 * ch : PROJ + (size_t)(kr0 + key) * INWP + C_KR + 8 * (ch - 16);
;             else if (MODE == 1) src = PROJ + (size_t)(kr0 + key) * INWP + C_DK + 128 * h + 8 * ch;
;             else src = PROJ + (size_t)(kr0 + key) * INWP + C_RK + 64 * h + 8 * ch;
;             glds16(src, (unsigned)__builtin_amdgcn_readfirstlane(kb_ + piece * 1024)); }
; #pragma unroll
;         for (int i = 0; i < 2; ++i) { const int piece = wave + 8 * i, p = 64 * piece + lane, st = p >> 5, key = 8 * (st >> 2) + ((p & 31) >> 2), col = 32 * (st & 3) + 8 * (p & 3); const bf16_t* src;
;             if (MODE == 0) src = KVM + (size_t)(kr0 + key) * 1024 + 256 * h + 128 + col;
;             else if (MODE == 1) src = PROJ + (size_t)(kr0 + key) * INWP + C_DV + 128 * h + col;
;             else src = PROJ + (size_t)(kr0 + key) * INWP + C_RV + 128 * h + col;
;             glds16(src, (unsigned)__builtin_amdgcn_readfirstlane(vb_ + piece * 1024)); }
;         if (MODE == 1) glds4((const int*)A->in[2] + rowbase + 64 * t + lane, (unsigned)__builtin_amdgcn_readfirstlane(lds0 + OFF_EXTRA + slot * 256));
;     };
;     f32x16 oacc[4];
; #pragma unroll
;     for (int c = 0; c < 4; ++c)
; #pragma unroll
;         for (int i = 0; i < 16; ++i) oacc[c][i] = 0.f;
;     float m_run = -INFINITY, l_run = 0.f;
; #pragma unroll
;     for (int s_ = 0; s_ < NS; ++s_) asm volatile("" : "+v"(qf[s_]));
;     asm volatile("" : "+v"(posq), "+v"(qmin), "+v"(lg2));
;     __syncthreads();
; #pragma unroll
;     for (int i = 0; i < NBUF - 1; ++i) if (i < ntile) dma_tile(i);
;     ...
;                 if (diag) {
;                     asm volatile("" ::: "memory");
; #pragma unroll
;                     for (int kb = 0; kb < 2; ++kb)
; #pragma unroll
	v_lshl_add_u64 v[18:19], v[18:19], 0, v[22:23]
	v_lshl_add_u64 v[26:27], v[26:27], 0, s[20:21]
	v_lshl_add_u64 v[30:31], v[30:31], 0, s[20:21]
	s_add_i32 s16, s27, s15
	s_mov_b32 s20, m0
	s_mov_b32 m0, s16
	s_nop 0
	global_load_lds_dwordx4 v[0:1], off
	s_mov_b32 m0, s20
	v_cndmask_b32_e32 v1, v13, v11, vcc
	v_cndmask_b32_e32 v0, v12, v10, vcc
	v_cmp_gt_i32_e32 vcc, 16, v37
	s_add_i32 s16, s34, s15
	s_mov_b32 s20, m0
	s_mov_b32 m0, s16
	s_nop 0
	global_load_lds_dwordx4 v[0:1], off
	s_mov_b32 m0, s20
	s_lshl_b32 s42, s17, 10
	v_cndmask_b32_e32 v1, v3, v19, vcc
	v_cndmask_b32_e32 v0, v2, v18, vcc
	s_add_i32 s16, s42, s15
	s_mov_b32 s17, m0
	s_mov_b32 m0, s16
	s_nop 0
	global_load_lds_dwordx4 v[0:1], off
	s_mov_b32 m0, s17
	s_add_i32 s15, s15, 0xc000
	v_lshlrev_b32_e32 v1, 4, v32
	s_add_i32 s16, s27, s15
	s_add_i32 s15, s34, s15
	v_lshlrev_b32_e32 v0, 8, v33
	v_and_b32_e32 v1, 0xc0, v1
	s_add_u32 s24, s10, s18
	v_add3_u32 v0, 16, v0, v1
	v_lshlrev_b32_e32 v1, 1, v32
	s_addc_u32 s25, s11, 0
	v_and_b32_e32 v1, 32, v1
	s_andn2_b32 s13, s13, 63
	v_add3_u32 v165, v0, v1, v39
	v_or_b32_e32 v0, s13, v164
	v_or_b32_e32 v1, 2, v0
	v_cmp_gt_i32_e64 s[46:47], v1, v64
	v_or_b32_e32 v1, 3, v0
	v_cmp_gt_i32_e64 s[48:49], v1, v64
	v_or_b32_e32 v1, 8, v0
	v_cmp_gt_i32_e64 s[50:51], v1, v64
	v_or_b32_e32 v1, 9, v0
	v_cmp_gt_i32_e64 s[52:53], v1, v64
	v_or_b32_e32 v1, 10, v0
	v_cmp_gt_i32_e64 s[54:55], v1, v64
	v_or_b32_e32 v1, 11, v0
	v_cmp_gt_i32_e64 s[56:57], v1, v64
	v_or_b32_e32 v1, 16, v0
	v_cmp_gt_i32_e64 s[58:59], v1, v64
	v_or_b32_e32 v1, 17, v0
	v_cmp_gt_i32_e64 s[60:61], v1, v64
	v_or_b32_e32 v1, 18, v0
	v_cmp_gt_i32_e64 s[62:63], v1, v64
	v_or_b32_e32 v1, 19, v0
	v_cmp_gt_i32_e64 s[64:65], v1, v64
	v_or_b32_e32 v1, 24, v0
	v_cmp_gt_i32_e64 s[66:67], v1, v64
	v_or_b32_e32 v1, 25, v0
	v_cmp_gt_i32_e64 s[68:69], v1, v64
	v_or_b32_e32 v1, 26, v0
	v_cmp_gt_i32_e64 s[70:71], v1, v64
	v_or_b32_e32 v1, 27, v0
	v_cmp_gt_i32_e64 s[72:73], v1, v64
	v_or_b32_e32 v1, 32, v0
	v_cmp_gt_i32_e64 s[74:75], v1, v64
	v_or_b32_e32 v1, 33, v0
	v_cmp_gt_i32_e64 s[76:77], v1, v64
	v_or_b32_e32 v1, 34, v0
	v_cmp_gt_i32_e64 s[78:79], v1, v64
	v_or_b32_e32 v1, 35, v0
	v_cmp_gt_i32_e64 s[80:81], v1, v64
	v_or_b32_e32 v1, 40, v0
	v_cmp_gt_i32_e64 s[82:83], v1, v64
	v_or_b32_e32 v1, 41, v0
	v_cmp_gt_i32_e64 s[84:85], v1, v64
	v_or_b32_e32 v1, 42, v0
	v_cmp_gt_i32_e64 s[86:87], v1, v64
	v_or_b32_e32 v1, 43, v0
	v_cmp_gt_i32_e64 s[88:89], v1, v64
	v_or_b32_e32 v1, 48, v0
	v_cmp_gt_i32_e64 s[90:91], v1, v64
	v_or_b32_e32 v1, 49, v0
	s_mov_b32 s17, m0
	s_mov_b32 m0, s16
	s_nop 0
	global_load_lds_dwordx4 v[26:27], off
	s_mov_b32 m0, s17
	v_cmp_gt_i32_e64 s[92:93], v1, v64
	v_or_b32_e32 v1, 50, v0
	s_mov_b32 s16, m0
	s_mov_b32 m0, s15
	s_nop 0
	global_load_lds_dwordx4 v[30:31], off
	s_mov_b32 m0, s16
	v_lshl_add_u64 v[150:151], s[8:9], 0, v[14:15]
	v_cmp_gt_i32_e64 s[94:95], v1, v64
	v_or_b32_e32 v1, 51, v0
	s_add_i32 s14, s14, 64
	s_add_i32 s12, s12, 64
	v_mov_b32_e32 v14, v177
	v_mov_b32_e32 v15, v177
	v_cmp_lt_i32_e64 s[2:3], 15, v29
	v_cmp_lt_i32_e64 s[4:5], 15, v36
	v_cmp_lt_i32_e64 s[6:7], 15, v37
	v_lshl_add_u64 v[146:147], s[8:9], 0, v[6:7]
	v_lshl_add_u64 v[148:149], s[24:25], 0, v[8:9]
	v_lshl_add_u64 v[152:153], s[24:25], 0, v[16:17]
	v_lshl_add_u64 v[154:155], s[8:9], 0, v[20:21]
	v_lshl_add_u64 v[156:157], s[24:25], 0, v[22:23]
	v_cmp_gt_i32_e64 s[8:9], v0, v64
	v_cmp_lt_i32_e64 s[44:45], v0, v64
	v_or_b32_e32 v166, s14, v38
	v_or_b32_e32 v167, s12, v38
	v_cmp_gt_i32_e64 s[96:97], v1, v64
	v_or_b32_e32 v65, 56, v0
	v_or_b32_e32 v66, 57, v0
	v_or_b32_e32 v67, 58, v0
	v_or_b32_e32 v68, 59, v0
	v_add_u32_e32 v168, 64, v34
	v_add_u32_e32 v169, 64, v35
	v_add_u32_e32 v170, 64, v25
	v_mov_b32_e32 v0, v177
	v_mov_b32_e32 v1, v177
	v_mov_b32_e32 v2, v177
	v_mov_b32_e32 v3, v177
	v_mov_b32_e32 v4, v177
	v_mov_b32_e32 v5, v177
	v_mov_b32_e32 v6, v177
	v_mov_b32_e32 v7, v177
	v_mov_b32_e32 v8, v177
	v_mov_b32_e32 v9, v177
	v_mov_b32_e32 v10, v177
	v_mov_b32_e32 v11, v177
	v_mov_b32_e32 v12, v177
	v_mov_b32_e32 v13, v177
	v_lshlrev_b32_e32 v176, 1, v24
	v_lshlrev_b32_e32 v158, 1, v28
	v_mov_b64_e32 v[30:31], v[14:15]
	v_mov_b64_e32 v[46:47], v[14:15]
	v_mov_b64_e32 v[62:63], v[14:15]
	v_mov_b64_e32 v[28:29], v[12:13]
	v_mov_b64_e32 v[26:27], v[10:11]
	v_mov_b64_e32 v[24:25], v[8:9]
	v_mov_b64_e32 v[22:23], v[6:7]
	v_mov_b64_e32 v[20:21], v[4:5]
	v_mov_b64_e32 v[18:19], v[2:3]
	v_mov_b64_e32 v[16:17], v[0:1]
	v_mov_b64_e32 v[44:45], v[12:13]
	v_mov_b64_e32 v[42:43], v[10:11]
	v_mov_b64_e32 v[40:41], v[8:9]
	v_mov_b64_e32 v[38:39], v[6:7]
	v_mov_b64_e32 v[36:37], v[4:5]
	v_mov_b64_e32 v[34:35], v[2:3]
	v_mov_b64_e32 v[32:33], v[0:1]
	v_mov_b64_e32 v[60:61], v[12:13]
	v_mov_b64_e32 v[58:59], v[10:11]
	v_mov_b64_e32 v[56:57], v[8:9]
	v_mov_b64_e32 v[54:55], v[6:7]
	v_mov_b64_e32 v[52:53], v[4:5]
	v_mov_b64_e32 v[50:51], v[2:3]
	v_mov_b64_e32 v[48:49], v[0:1]
	v_cmp_gt_i32_e64 s[10:11], v65, v64
	v_cmp_gt_i32_e64 s[12:13], v66, v64
	v_cmp_gt_i32_e64 s[14:15], v67, v64
	v_cmp_gt_i32_e64 s[16:17], v68, v64

; template <int MODE>
; __device__ __forceinline__ void flash_unit(ArgsP A, int l, int b, int h, int qb, unsigned char* lds) {
;     ...
;         const bf16_t* qp = PROJ + (size_t)qrow * INWP + C_RQ + 64 * h + 8 * hh;
; #pragma unroll
;         for (int s = 0; s < NS; ++s) qf[s] = __builtin_bit_cast(bf16x8, *(const u32x4*)(qp + 16 * s));
;     }
;     int posq = 0, qmin = 0; float bfar = 0.f;
;     if (MODE == 1) {
;         const int* pos = (const int*)A->in[2];
;         if (tid < 129) { int n = tid; int bucket;
;             if (n < 16) bucket = n; else { const float nf = (float)n; int lg = 16 + (int)(logf(nf / 16.f) / 2.0794415416798357f * 16.f); bucket = lg < 31 ? lg : 31; }
;             if (tid == 128) bucket = 31;
;             btab[tid] = A->in[3][bucket * 4 + h] * LOG2E; }
;         posq = pos[qrow];
;         int mn = posq;
; #pragma unroll
;         for (int o = 1; o < 64; o <<= 1) { const int other = __shfl_xor(mn, o); mn = other < mn ? other : mn; }
;         qmin = mn;
;     }
;     float lg2 = 0.f;
;     if (MODE == 2) lg2 = log2f(1.f - exp2f(-5.f - (float)h));
;     const unsigned lds0 = (unsigned)(uintptr_t)lds;
;     int kbase[4];
; #pragma unroll
;     for (int bsel = 0; bsel < 4; ++bsel) { const int ch = 2 * bsel + hh + (MODE == 1 ? 8 * map : 0), xr = (MODE == 1) ? (q32 & 15) : ((q32 >> 1) & 7); kbase[bsel] = (q32 * KCH + (ch ^ xr)) * 16; }
;     auto dma_tile = [&](int t) {
;         const int kr0 = rowbase + 64 * t;
;         const int slot = t % NBUF; const unsigned kb_ = lds0 + slot * KBYTES, vb_ = lds0 + NBUF * KBYTES + slot * VBYTES;
; #pragma unroll
;         for (int i = 0; i < NKI; ++i) { const int piece = wave + 8 * i, p = 64 * piece + lane, key = p / KCH, cs = p % KCH;
;             const int ch = cs ^ (MODE == 1 ? (key & 15) : ((key >> 1) & 7)); const bf16_t* src;
; template <int PHM, int MIXM>
; __global__ void __launch_bounds__(512, 2) mega(Args Aval) {
;     ...
;             for (int r2 = 0; r2 < ((PROBE_DUP & 16) ? 2 : 1); ++r2) if (MIXM & 1) QLOOP2(0, r2, 256, { const int L = 15 - (item >> 4), r = item & 15; flash_unit<0>(A, l, r >> 2, r & 3, L, lds); })
;             for (int r2 = 0; r2 < ((PROBE_DUP & 32) ? 2 : 1); ++r2) if (MIXM & 2) QLOOP2(1, r2, 256, { const int L = 15 - (item >> 4), r = item & 15; flash_unit<2>(A, l, r >> 2, r & 3, L, lds); })
.LBB0_765:
	s_or_b64 exec, exec, s[2:3]
	s_waitcnt lgkmcnt(0)
	s_barrier
	ds_read_b32 v0, v177 offset:8
	s_mov_b64 s[2:3], -1
	s_waitcnt lgkmcnt(0)
	s_barrier
	v_cmp_gt_i32_e32 vcc, s68, v0
	v_readfirstlane_b32 s5, v0
	s_cbranch_vccz .LBB0_760
	v_readfirstlane_b32 s100, v238
	s_cmp_lt_u32 s100, 0x100
	s_cbranch_scc1 .Lprio_skip_ret
	s_setprio 1
.Lprio_skip_ret:
	v_mov_b32_e32 v10, v238
	s_load_dwordx2 s[2:3], s[26:27], 0x148
	v_readfirstlane_b32 s15, v10
	s_and_b32 s4, s5, 3
	s_ashr_i32 s16, s15, 6
	v_and_b32_e32 v4, 31, v10
	s_waitcnt lgkmcnt(0)
	s_add_u32 s6, s2, 0x18f90000
	s_addc_u32 s7, s3, 0
	s_lshl_b32 s8, s5, 10
	s_lshl_b32 s5, s5, 4
	s_and_b32 s17, s8, 0x3000
	s_and_b32 s5, s5, 0xffffff00
	s_lshl_b32 s8, s16, 5
	s_sub_i32 s8, s8, s5
	s_add_i32 s13, s8, 0xf00
	v_or_b32_e32 v164, s13, v4
	v_add_u32_e32 v160, s17, v164
	v_mov_b64_e32 v[0:1], s[6:7]
	v_bfe_u32 v11, v10, 5, 1
	v_mad_i64_i32 v[162:163], s[8:9], v160, s35, v[0:1]
	s_lshl_b32 s18, s4, 7
	v_lshl_add_u64 v[2:3], v[162:163], 0, s[18:19]
	v_lshlrev_b32_e32 v176, 4, v11
	v_lshl_add_u64 v[2:3], v[2:3], 0, v[176:177]
	global_load_dwordx4 v[144:147], v[2:3], off offset:2432
	global_load_dwordx4 v[148:151], v[2:3], off offset:2464
	global_load_dwordx4 v[152:155], v[2:3], off offset:2496
	global_load_dwordx4 v[156:159], v[2:3], off offset:2528
	v_cvt_f32_ubyte0_e32 v5, s4
	v_sub_f32_e32 v5, 0xc0a00000, v5
	s_mov_b32 s8, 0xc2fc0000
	v_cmp_gt_f32_e32 vcc, s8, v5
	v_mov_b32_e32 v9, 0x42800000
	v_lshrrev_b32_e32 v7, 1, v10
	v_cndmask_b32_e32 v9, 0, v9, vcc
	v_add_f32_e32 v5, v5, v9
	v_exp_f32_e32 v5, v5
	s_sub_i32 s5, 0x1000, s5
	v_lshlrev_b32_e32 v192, 7, v4
	v_bitop3_b32 v4, v11, v7, 7 bitop3:0x78
	v_mov_b32_e32 v13, s15
	s_movk_i32 s8, 0xffc0
	s_lshr_b32 s12, s5, 6
	v_lshlrev_b32_e32 v193, 4, v4
	v_bfi_b32 v4, s8, v13, v10
	s_and_b64 s[8:9], vcc, exec
	s_cselect_b32 s5, 0xffffffc0, 0
	s_ashr_i32 s8, s13, 31
	v_ldexp_f32 v5, v5, s5
	s_lshr_b32 s5, s8, 26
	s_add_i32 s5, s5, s13
	v_sub_f32_e32 v5, 1.0, v5
	s_add_i32 s5, s5, 31
	s_mov_b32 s8, 0x800000
	v_cmp_gt_f32_e32 vcc, s8, v5
	s_ashr_i32 s13, s5, 6
	s_and_b64 s[8:9], vcc, exec
	s_cselect_b32 s5, 32, 0
	v_ldexp_f32 v5, v5, s5
	v_bfe_u32 v8, v10, 1, 3
	v_log_f32_e32 v5, v5
	v_bitop3_b32 v7, v11, v8, 2 bitop3:0x36
	v_lshlrev_b32_e32 v194, 4, v7
	v_mov_b32_e32 v7, 0x42000000
	s_ashr_i32 s8, s15, 31
	v_bitop3_b32 v12, v11, v8, 4 bitop3:0x36
	v_bitop3_b32 v8, v11, v8, 6 bitop3:0x36
	v_cndmask_b32_e32 v7, 0, v7, vcc
	s_lshr_b32 s5, s8, 29
	v_mov_b32_e32 v2, v177
	v_mov_b32_e32 v3, v177
	v_lshlrev_b32_e32 v196, 4, v8
	v_add_u32_e32 v8, s5, v4
	v_sub_f32_e32 v197, v5, v7
	v_lshlrev_b32_e32 v195, 4, v12
	s_lshl_b32 s14, s16, 10
	v_ashrrev_i32_e32 v12, 3, v8
	v_and_b32_e32 v8, 0x1ffffff8, v8
	s_cmp_lg_u32 16, -1
	v_sub_u32_e32 v8, v4, v8
	v_lshrrev_b32_e32 v9, 1, v12
	v_and_b32_e32 v6, 63, v10
	s_cselect_b32 s20, 16, 0
	v_bitop3_b32 v8, v9, v8, 7 bitop3:0x6c
	s_movk_i32 s8, 0x60
	s_add_i32 s16, s16, 8
	v_lshlrev_b32_e32 v166, 3, v8
	v_add_u32_e32 v14, s17, v12
	v_ashrrev_i32_e32 v167, 31, v166
	s_ashr_i32 s5, s15, 4
	s_and_b32 s21, s5, -8
	s_lshl_b32 s5, s16, 2
	s_add_i32 s15, s14, s20
	s_and_b32 s22, s5, -8
	s_waitcnt vmcnt(3)
	s_waitcnt vmcnt(2)
	s_waitcnt vmcnt(1)
	s_waitcnt vmcnt(0)
	s_nop 0
	v_lshlrev_b32_e32 v2, 3, v10
	v_and_b32_e32 v13, 24, v2
	v_and_or_b32 v2, v4, s8, v13
	v_lshl_or_b32 v4, s16, 6, v6
	v_and_or_b32 v16, v4, s8, v13
	v_mad_i64_i32 v[4:5], s[8:9], v14, s35, v[0:1]
	v_lshl_add_u64 v[4:5], v[4:5], 0, s[18:19]
	v_lshlrev_b64 v[6:7], 1, v[166:167]
	v_bfe_u32 v3, v10, 2, 3
	v_lshl_add_u64 v[4:5], v[4:5], 0, v[6:7]
	v_lshl_add_u64 v[4:5], v[4:5], 0, s[88:89]
	v_or_b32_e32 v8, s17, v3
	s_barrier
; template <int MODE>
; __device__ __forceinline__ void flash_unit(ArgsP A, int l, int b, int h, int qb, unsigned char* lds) {
;     ...
;     auto dma_tile = [&](int t) {
;         const int kr0 = rowbase + 64 * t;
;         const int slot = t % NBUF; const unsigned kb_ = lds0 + slot * KBYTES, vb_ = lds0 + NBUF * KBYTES + slot * VBYTES;
; #pragma unroll
;         for (int i = 0; i < NKI; ++i) { const int piece = wave + 8 * i, p = 64 * piece + lane, key = p / KCH, cs = p % KCH;
;             const int ch = cs ^ (MODE == 1 ? (key & 15) : ((key >> 1) & 7)); const bf16_t* src;
;             if (MODE == 0) src = (ch < 16) ? KVM + (size_t)(kr0 + key) * 1024 + 256 * h + 8 * ch : PROJ + (size_t)(kr0 + key) * INWP + C_KR + 8 * (ch - 16);
;             else if (MODE == 1) src = PROJ + (size_t)(kr0 + key) * INWP + C_DK + 128 * h + 8 * ch;
;             else src = PROJ + (size_t)(kr0 + key) * INWP + C_RK + 64 * h + 8 * ch;
;             glds16(src, (unsigned)__builtin_amdgcn_readfirstlane(kb_ + piece * 1024)); }
; #pragma unroll
;         for (int i = 0; i < 2; ++i) { const int piece = wave + 8 * i, p = 64 * piece + lane, st = p >> 5, key = 8 * (st >> 2) + ((p & 31) >> 2), col = 32 * (st & 3) + 8 * (p & 3); const bf16_t* src;
;             if (MODE == 0) src = KVM + (size_t)(kr0 + key) * 1024 + 256 * h + 128 + col;
;             else if (MODE == 1) src = PROJ + (size_t)(kr0 + key) * INWP + C_DV + 128 * h + col;
;             else src = PROJ + (size_t)(kr0 + key) * INWP + C_RV + 128 * h + col;
;             glds16(src, (unsigned)__builtin_amdgcn_readfirstlane(vb_ + piece * 1024)); }
;         if (MODE == 1) glds4((const int*)A->in[2] + rowbase + 64 * t + lane, (unsigned)__builtin_amdgcn_readfirstlane(lds0 + OFF_EXTRA + slot * 256));
;     };
;     f32x16 oacc[4];
; #pragma unroll
;     for (int c = 0; c < 4; ++c)
; #pragma unroll
;         for (int i = 0; i < 16; ++i) oacc[c][i] = 0.f;
;     float m_run = -INFINITY, l_run = 0.f;
; #pragma unroll
;     for (int s_ = 0; s_ < NS; ++s_) asm volatile("" : "+v"(qf[s_]));
;     asm volatile("" : "+v"(posq), "+v"(qmin), "+v"(lg2));
;     __syncthreads();
; #pragma unroll
;     for (int i = 0; i < NBUF - 1; ++i) if (i < ntile) dma_tile(i);
	s_mov_b32 s5, m0
	s_mov_b32 m0, s15
	s_nop 0
	global_load_lds_dwordx4 v[4:5], off
	s_mov_b32 m0, s5
	v_add_u32_e32 v4, s21, v8
	v_mad_i64_i32 v[4:5], s[8:9], v4, s35, v[0:1]
	s_lshl_b32 s8, s4, 8
	s_mov_b32 s9, s19
	v_lshl_add_u64 v[4:5], v[4:5], 0, s[8:9]
	v_lshlrev_b32_e32 v176, 1, v2
	v_lshl_add_u64 v[4:5], v[4:5], 0, v[176:177]
	v_lshl_add_u64 v[4:5], v[4:5], 0, s[90:91]
	s_add_i32 s23, s20, 0x8000
	s_add_i32 s4, s14, s23
	s_mov_b32 s5, m0
	s_mov_b32 m0, s4
	s_nop 0
	global_load_lds_dwordx4 v[4:5], off
	s_mov_b32 m0, s5
	v_add_u32_e32 v4, s22, v8
	v_mad_i64_i32 v[4:5], s[4:5], v4, s35, v[0:1]
	v_lshl_add_u64 v[4:5], v[4:5], 0, s[8:9]
	v_lshlrev_b32_e32 v8, 1, v16
	v_mov_b32_e32 v9, v177
	s_lshl_b32 s16, s16, 10
	v_lshl_add_u64 v[4:5], v[4:5], 0, v[8:9]
	v_lshl_add_u64 v[4:5], v[4:5], 0, s[90:91]
	s_add_i32 s4, s16, s23
	s_or_b32 s23, s17, 64
	s_mov_b32 s5, m0
	s_mov_b32 m0, s4
	s_nop 0
	global_load_lds_dwordx4 v[4:5], off
	s_mov_b32 m0, s5
	v_add_u32_e32 v4, s23, v12
	v_mad_i64_i32 v[4:5], s[4:5], v4, s35, v[0:1]
	v_lshl_add_u64 v[4:5], v[4:5], 0, s[18:19]
	v_lshl_add_u64 v[4:5], v[4:5], 0, v[6:7]
	v_lshl_add_u64 v[4:5], v[4:5], 0, s[88:89]
	v_or_b32_e32 v15, s23, v3
	s_add_i32 s4, s15, 0x2000
	s_mov_b32 s5, m0
	s_mov_b32 m0, s4
	s_nop 0
	global_load_lds_dwordx4 v[4:5], off
	s_mov_b32 m0, s5
	v_add_u32_e32 v4, s21, v15
	v_mad_i64_i32 v[4:5], s[4:5], v4, s35, v[0:1]
	v_lshl_add_u64 v[4:5], v[4:5], 0, s[8:9]
	v_lshl_add_u64 v[4:5], v[4:5], 0, v[176:177]
	v_lshl_add_u64 v[4:5], v[4:5], 0, s[90:91]
	s_add_i32 s23, s20, 0xc000
	s_add_i32 s4, s14, s23
	s_mov_b32 s5, m0
	s_mov_b32 m0, s4
	s_nop 0
	global_load_lds_dwordx4 v[4:5], off
	s_mov_b32 m0, s5
	v_add_u32_e32 v4, s22, v15
	v_mad_i64_i32 v[4:5], s[4:5], v4, s35, v[0:1]
	v_lshl_add_u64 v[4:5], v[4:5], 0, s[8:9]
	v_lshl_add_u64 v[4:5], v[4:5], 0, v[8:9]
	v_lshl_add_u64 v[4:5], v[4:5], 0, s[90:91]
	s_add_i32 s4, s16, s23
	s_or_b32 s23, s17, 0x80
	s_mov_b32 s5, m0
	s_mov_b32 m0, s4
	s_nop 0
	global_load_lds_dwordx4 v[4:5], off
	s_mov_b32 m0, s5
	v_add_u32_e32 v4, s23, v12
	v_mad_i64_i32 v[4:5], s[4:5], v4, s35, v[0:1]
	v_lshl_add_u64 v[4:5], v[4:5], 0, s[18:19]
	v_lshl_add_u64 v[4:5], v[4:5], 0, v[6:7]
	v_lshl_add_u64 v[4:5], v[4:5], 0, s[88:89]
	v_or_b32_e32 v6, s23, v3
	s_add_i32 s4, s15, 0x4000
	s_mov_b32 s5, m0
	s_mov_b32 m0, s4
	s_nop 0
	global_load_lds_dwordx4 v[4:5], off
	s_mov_b32 m0, s5
	v_add_u32_e32 v4, s21, v6
	v_mad_i64_i32 v[4:5], s[4:5], v4, s35, v[0:1]
	v_lshl_add_u64 v[4:5], v[4:5], 0, s[8:9]
	v_lshl_add_u64 v[4:5], v[4:5], 0, v[176:177]
	v_lshl_add_u64 v[4:5], v[4:5], 0, s[90:91]
	s_add_i32 s20, s20, 0x10000
	s_add_i32 s4, s14, s20
	s_mov_b32 s5, m0
	s_mov_b32 m0, s4
	s_nop 0
	global_load_lds_dwordx4 v[4:5], off
	s_mov_b32 m0, s5
	v_add_u32_e32 v4, s22, v6
	v_mad_i64_i32 v[0:1], s[4:5], v4, s35, v[0:1]
	v_lshl_add_u64 v[0:1], v[0:1], 0, s[8:9]
	v_lshl_add_u64 v[0:1], v[0:1], 0, v[8:9]
	s_add_i32 s4, s16, s20
	v_lshl_add_u64 v[0:1], v[0:1], 0, s[90:91]
	s_mov_b32 s5, m0
	s_mov_b32 m0, s4
	s_nop 0
	global_load_lds_dwordx4 v[0:1], off
	s_mov_b32 m0, s5
	s_add_u32 s4, s6, s18
	v_lshlrev_b32_e32 v1, 4, v10
	s_addc_u32 s5, s7, 0
	v_lshlrev_b32_e32 v0, 8, v11
	v_and_b32_e32 v1, 0xc0, v1
	s_add_u32 s6, s6, s8
	v_add3_u32 v0, 16, v0, v1
	v_lshlrev_b32_e32 v1, 1, v10
	s_addc_u32 s7, s7, 0
	s_or_b32 s8, s17, 0xc0
	v_and_b32_e32 v1, 32, v1
	s_add_i32 s9, s8, s22
	s_add_i32 s8, s8, s21
	v_add_u32_e32 v202, 0xc0, v14
	v_mov_b32_e32 v14, v177
	v_mov_b32_e32 v15, v177
	v_lshlrev_b32_e32 v198, 2, v11
	v_add3_u32 v199, v0, v1, v13
	v_or_b32_e32 v200, s9, v3
	v_or_b32_e32 v201, s8, v3
	v_lshlrev_b32_e32 v176, 1, v2
	v_mov_b32_e32 v0, v177
	v_mov_b32_e32 v1, v177
	v_mov_b32_e32 v2, v177
	v_mov_b32_e32 v3, v177
	v_mov_b32_e32 v4, v177
	v_mov_b32_e32 v5, v177
	v_mov_b32_e32 v6, v177
	v_mov_b32_e32 v7, v177
	v_mov_b32_e32 v8, v177
	v_mov_b32_e32 v10, v177
	v_mov_b32_e32 v11, v177
	v_mov_b32_e32 v12, v177
	v_mov_b32_e32 v13, v177
	v_lshlrev_b32_e32 v168, 1, v16
	v_mov_b64_e32 v[30:31], v[14:15]
	v_mov_b64_e32 v[46:47], v[14:15]
	v_mov_b64_e32 v[62:63], v[14:15]
	s_mov_b32 s10, 0
	s_mov_b32 s11, -1
	v_ashrrev_i32_e32 v161, 31, v160
	v_mov_b32_e32 v165, v164
	v_mov_b32_e32 v64, v164
	v_mov_b32_e32 v65, v164
	v_mov_b32_e32 v66, v164
	v_mov_b32_e32 v67, v164
	v_mov_b32_e32 v68, v164
	v_mov_b32_e32 v69, v164
	v_mov_b32_e32 v70, v164
	v_mov_b32_e32 v71, v164
	v_mov_b32_e32 v72, v164
	v_mov_b32_e32 v73, v164
	v_mov_b32_e32 v74, v164
	v_mov_b32_e32 v75, v164
	s_add_i32 s17, s12, -2
	s_mov_b32 s24, 0
	v_mov_b32_e32 v203, v164
	v_mov_b32_e32 v76, v164
	v_mov_b32_e32 v77, v164
	v_mov_b32_e32 v78, v164
	v_mov_b32_e32 v79, v164
	v_mov_b64_e32 v[28:29], v[12:13]
	v_mov_b64_e32 v[26:27], v[10:11]
	v_mov_b64_e32 v[24:25], v[8:9]
	v_mov_b64_e32 v[22:23], v[6:7]
	v_mov_b64_e32 v[20:21], v[4:5]
	v_mov_b64_e32 v[18:19], v[2:3]
	v_mov_b64_e32 v[16:17], v[0:1]
	v_mov_b64_e32 v[44:45], v[12:13]
	v_mov_b64_e32 v[42:43], v[10:11]
	v_mov_b64_e32 v[40:41], v[8:9]
	v_mov_b64_e32 v[38:39], v[6:7]
	v_mov_b64_e32 v[36:37], v[4:5]
	v_mov_b64_e32 v[34:35], v[2:3]
	v_mov_b64_e32 v[32:33], v[0:1]
	v_mov_b64_e32 v[60:61], v[12:13]
	v_mov_b64_e32 v[58:59], v[10:11]
	v_mov_b64_e32 v[56:57], v[8:9]
	v_mov_b64_e32 v[54:55], v[6:7]
	v_mov_b64_e32 v[52:53], v[4:5]
	v_mov_b64_e32 v[50:51], v[2:3]
	v_mov_b64_e32 v[48:49], v[0:1]
	s_branch .LBB0_769

; #define QLOOP2(qi_, r2_, n_, ...) for (;;) { if (tid == 0) s_item = (int)atomicAdd(ctr + 64 * (qi_) + 32 * (r2_), 1u); __syncthreads(); const int item = s_item; __syncthreads(); if (item >= (n_)) break; __VA_ARGS__ }
; template <int MODE>
; __device__ __forceinline__ void flash_unit(ArgsP A, int l, int b, int h, int qb, unsigned char* lds) {
;     ...
;         const float csc = 0.125f * LOG2E;
;         const bf16_t* qp = PROJ + (size_t)qrow * INWP + C_DQ + 128 * h + 64 * map + 8 * hh;
; #pragma unroll
;         for (int s = 0; s < NS; ++s) qf[s] = scale8(*(const u32x4*)(qp + 16 * s), csc);
;     } else {
;         const bf16_t* qp = PROJ + (size_t)qrow * INWP + C_RQ + 64 * h + 8 * hh;
; #pragma unroll
;         for (int s = 0; s < NS; ++s) qf[s] = __builtin_bit_cast(bf16x8, *(const u32x4*)(qp + 16 * s));
;     }
;     int posq = 0, qmin = 0; float bfar = 0.f;
;     if (MODE == 1) {
;         const int* pos = (const int*)A->in[2];
;         if (tid < 129) { int n = tid; int bucket;
;             if (n < 16) bucket = n; else { const float nf = (float)n; int lg = 16 + (int)(logf(nf / 16.f) / 2.0794415416798357f * 16.f); bucket = lg < 31 ? lg : 31; }
;             if (tid == 128) bucket = 31;
;             btab[tid] = A->in[3][bucket * 4 + h] * LOG2E; }
; template <int PHM, int MIXM>
; __global__ void __launch_bounds__(512, 2) mega(Args Aval) {
;     ...
;             for (int r2 = 0; r2 < ((PROBE_DUP & 16) ? 2 : 1); ++r2) if (MIXM & 1) QLOOP2(0, r2, 256, { const int L = 15 - (item >> 4), r = item & 15; flash_unit<0>(A, l, r >> 2, r & 3, L, lds); })
;             for (int r2 = 0; r2 < ((PROBE_DUP & 32) ? 2 : 1); ++r2) if (MIXM & 2) QLOOP2(1, r2, 256, { const int L = 15 - (item >> 4), r = item & 15; flash_unit<2>(A, l, r >> 2, r & 3, L, lds); })
;             for (int r2 = 0; r2 < ((PROBE_DUP & 64) ? 2 : 1); ++r2) if (MIXM & 8) QLOOP2(2, r2, 256, { s5_unit(A, l, item, lds, wave, lane); })
;             for (int r2 = 0; r2 < ((PROBE_DUP & 128) ? 2 : 1); ++r2) if (MIXM & 4) QLOOP2(3, r2, 512, { const int L = 31 - (item >> 4), r = item & 15; flash_unit<1>(A, l, r >> 2, r & 3, L, lds); })
.LBB0_801:
	s_or_b64 exec, exec, s[2:3]
	s_waitcnt lgkmcnt(0)
	s_barrier
	ds_read_b32 v0, v177 offset:8
	s_movk_i32 s2, 0x1ff
	s_waitcnt lgkmcnt(0)
	s_barrier
	v_cmp_lt_i32_e32 vcc, s2, v0
	v_readfirstlane_b32 s4, v0
	s_mov_b64 s[2:3], -1
	s_cbranch_vccnz .LBB0_796
	v_readfirstlane_b32 s100, v238
	s_cmp_lt_u32 s100, 0x100
	s_cbranch_scc1 .Lprio_skip_diff
	s_setprio 1
.Lprio_skip_diff:
	v_mov_b32_e32 v18, v238
	s_load_dwordx2 s[2:3], s[26:27], 0x148
	v_readfirstlane_b32 s24, v18
	s_ashr_i32 s17, s4, 4
	s_and_b32 s25, s4, 3
	s_ashr_i32 s14, s24, 6
	s_waitcnt lgkmcnt(0)
	s_add_u32 s10, s2, 0x18f90000
	v_writelane_b32 v255, s2, 15
	s_addc_u32 s11, s3, 0
	s_lshl_b32 s29, s14, 5
	s_lshl_b32 s9, s17, 7
	s_and_b32 s15, s29, 0x60
	s_sub_i32 s8, s15, s9
	v_and_b32_e32 v130, 31, v18
	v_writelane_b32 v255, s3, 16
	s_lshl_b32 s2, s4, 10
	s_addk_i32 s8, 0xf80
	s_and_b32 s16, s2, 0x3000
	v_or_b32_e32 v16, s8, v130
	v_add_u32_e32 v156, s16, v16
	v_mov_b64_e32 v[0:1], s[10:11]
	s_ashr_i32 s30, s24, 8
	v_mad_u64_u32 v[0:1], s[2:3], v156, s35, v[0:1]
	s_lshl_b32 s18, s25, 8
	s_lshl_b32 s2, s30, 6
	v_bfe_u32 v17, v18, 5, 1
	v_lshl_add_u64 v[0:1], v[0:1], 0, s[18:19]
	s_ashr_i32 s3, s2, 31
	v_lshl_add_u64 v[0:1], s[2:3], 1, v[0:1]
	v_lshlrev_b32_e32 v128, 4, v17
	v_mov_b32_e32 v129, v177
	v_lshl_add_u64 v[0:1], v[0:1], 0, v[128:129]
	s_mov_b64 s[2:3], 0x1580
	v_lshl_add_u64 v[2:3], v[0:1], 0, s[2:3]
	v_add_co_u32_e32 v0, vcc, 0x1000, v0
	s_movk_i32 s4, 0x81
	s_nop 0
	v_addc_co_u32_e32 v1, vcc, 0, v1, vcc
	global_load_dwordx4 v[12:15], v[0:1], off offset:1408
	global_load_dwordx4 v[8:11], v[2:3], off offset:32
	global_load_dwordx4 v[4:7], v[2:3], off offset:64
	s_nop 0
	global_load_dwordx4 v[0:3], v[2:3], off offset:96
	s_load_dwordx2 s[2:3], s[26:27], 0x10
	v_cmp_gt_i32_e32 vcc, s4, v18
	s_and_saveexec_b64 s[4:5], vcc
	s_cbranch_execz .LBB0_806
	v_cmp_lt_i32_e32 vcc, 15, v18
	v_mov_b32_e32 v19, v18
	s_and_saveexec_b64 s[6:7], vcc
	s_cbranch_execz .LBB0_805
	v_cvt_f32_u32_e32 v19, v18
	s_mov_b32 s18, 0x800000
	v_mul_f32_e32 v19, 0x3d800000, v19
	v_cmp_gt_f32_e32 vcc, s18, v19
	s_mov_b32 s18, 0x3f317217
	s_nop 0
	v_cndmask_b32_e64 v20, 0, 32, vcc
	v_ldexp_f32 v19, v19, v20
	v_log_f32_e32 v19, v19
	v_mov_b32_e32 v20, 0x41b17218
	v_cndmask_b32_e32 v20, 0, v20, vcc
	v_mul_f32_e32 v21, 0x3f317217, v19
	v_fma_f32 v21, v19, s18, -v21
	v_fmac_f32_e32 v21, 0x3377d1cf, v19
	s_mov_b32 s18, 0x7f800000
	v_fmac_f32_e32 v21, 0x3f317217, v19
	v_cmp_lt_f32_e64 vcc, |v19|, s18
	s_mov_b32 s18, 0x40051592
	s_nop 0
	v_cndmask_b32_e32 v19, v19, v21, vcc
	v_sub_f32_e32 v19, v19, v20
	v_div_scale_f32 v20, s[20:21], s18, s18, v19
	v_rcp_f32_e32 v21, v20
	v_div_scale_f32 v22, vcc, v19, s18, v19
	v_fma_f32 v23, -v20, v21, 1.0
	v_fmac_f32_e32 v21, v23, v21
	v_mul_f32_e32 v23, v22, v21
	v_fma_f32 v24, -v20, v23, v22
	v_fmac_f32_e32 v23, v24, v21
	v_fma_f32 v20, -v20, v23, v22
	v_div_fmas_f32 v20, v20, v21, v23
	v_div_fixup_f32 v19, v20, s18, v19
	v_mul_f32_e32 v19, 0x41800000, v19
	v_cvt_i32_f32_e32 v19, v19
	v_min_i32_e32 v19, 15, v19
	v_add_u32_e32 v19, 16, v19
